# grid barrier: the globally-last XCD leader bumps every XCD's release word itself (one hop fewer for non-leaders); other leaders no longer release
# speedup vs baseline: 1.0036x; 1.0036x over previous
; __device__ __forceinline__ unsigned xb_ld(unsigned* p)              { return __hip_atomic_load(p, __ATOMIC_RELAXED, __HIP_MEMORY_SCOPE_AGENT); }
; __device__ __forceinline__ unsigned xb_add(unsigned* p, unsigned v) { return __hip_atomic_fetch_add(p, v, __ATOMIC_RELAXED, __HIP_MEMORY_SCOPE_AGENT); }
; #define XB_SPIN(cond, bar) do { unsigned _sp = 0; while (cond) { __builtin_amdgcn_s_sleep(1); \
;     if ((++_sp & 255u) == 0u) { if (xb_ld(&(bar)[XB_TMO])) break; if (_sp > XB_SPIN_CAP) { atomicAdd(&(bar)[XB_TMO], 1u); break; } } } } while (0)
; template <bool FLUSH> __device__ __forceinline__ void xcd_barrier(const XcdBarrier& b) {
;     ...
;             const unsigned og = xb_add(&bar[XB_TOP], 1u);
;             const unsigned tg = og / nx;
;             if (og + 1u == (tg + 1u) * nx) xb_add(&bar[XB_TOPGEN], 1u);
;             else XB_SPIN(xb_ld(&bar[XB_TOPGEN]) == tg, bar);
;             __builtin_amdgcn_fence(__ATOMIC_ACQUIRE, "agent");
;             xb_add(&bar[XB_XGEN(b.x)], 1u);
;             asm volatile("s_waitcnt vmcnt(0)" ::: "memory");
.LBB0_113:
	s_or_b64 exec, exec, s[8:9]
	s_and_saveexec_b64 s[6:7], s[10:11]
	s_cbranch_execz .LBB0_115
	v_mov_b32_e32 v2, 1
	global_atomic_add v[0:1], v2, off
	s_add_u32 s98, s42, 0x3500
	v_cmp_eq_u32_e32 vcc, s98, v0
	s_and_saveexec_b64 s[100:101], vcc
	s_cbranch_execz .Lxgen_skip_0
	v_mov_b32_e32 v3, 0x2400
	global_atomic_add v3, v2, s[42:43]
	global_atomic_add v3, v2, s[42:43] offset:256
	global_atomic_add v3, v2, s[42:43] offset:512
	global_atomic_add v3, v2, s[42:43] offset:768
	global_atomic_add v3, v2, s[42:43] offset:1024
	global_atomic_add v3, v2, s[42:43] offset:1280
	global_atomic_add v3, v2, s[42:43] offset:1536
	global_atomic_add v3, v2, s[42:43] offset:1792
	global_atomic_add v3, v2, s[42:43] offset:2048
	global_atomic_add v3, v2, s[42:43] offset:2304
	global_atomic_add v3, v2, s[42:43] offset:2560
	global_atomic_add v3, v2, s[42:43] offset:2816
	global_atomic_add v3, v2, s[42:43] offset:3072
	global_atomic_add v3, v2, s[42:43] offset:3328
	global_atomic_add v3, v2, s[42:43] offset:3584
	global_atomic_add v3, v2, s[42:43] offset:3840
.Lxgen_skip_0:
	s_or_b64 exec, exec, s[100:101]
.LBB0_115:
	s_or_b64 exec, exec, s[6:7]
	v_mov_b32_e32 v0, 0x2000
	v_mov_b32_e32 v1, 1
	s_waitcnt vmcnt(0)
	buffer_inv sc1
	s_waitcnt vmcnt(0)

; __device__ __forceinline__ unsigned xb_ld(unsigned* p)              { return __hip_atomic_load(p, __ATOMIC_RELAXED, __HIP_MEMORY_SCOPE_AGENT); }
; __device__ __forceinline__ unsigned xb_add(unsigned* p, unsigned v) { return __hip_atomic_fetch_add(p, v, __ATOMIC_RELAXED, __HIP_MEMORY_SCOPE_AGENT); }
; #define XB_SPIN(cond, bar) do { unsigned _sp = 0; while (cond) { __builtin_amdgcn_s_sleep(1); \
;     if ((++_sp & 255u) == 0u) { if (xb_ld(&(bar)[XB_TMO])) break; if (_sp > XB_SPIN_CAP) { atomicAdd(&(bar)[XB_TMO], 1u); break; } } } } while (0)
; template <bool FLUSH> __device__ __forceinline__ void xcd_barrier(const XcdBarrier& b) {
;     ...
;             const unsigned og = xb_add(&bar[XB_TOP], 1u);
;             const unsigned tg = og / nx;
;             if (og + 1u == (tg + 1u) * nx) xb_add(&bar[XB_TOPGEN], 1u);
;             else XB_SPIN(xb_ld(&bar[XB_TOPGEN]) == tg, bar);
;             __builtin_amdgcn_fence(__ATOMIC_ACQUIRE, "agent");
;             xb_add(&bar[XB_XGEN(b.x)], 1u);
;             asm volatile("s_waitcnt vmcnt(0)" ::: "memory");
.LBB0_2225:
	s_or_b64 exec, exec, s[6:7]
	s_and_saveexec_b64 s[4:5], s[8:9]
	s_cbranch_execz .LBB0_2227
	v_mov_b32_e32 v2, 1
	global_atomic_add v[0:1], v2, off
	s_add_u32 s98, s42, 0x3500
	v_cmp_eq_u32_e32 vcc, s98, v0
	s_and_saveexec_b64 s[100:101], vcc
	s_cbranch_execz .Lxgen_skip_17
	v_mov_b32_e32 v3, 0x2400
	global_atomic_add v3, v2, s[42:43]
	global_atomic_add v3, v2, s[42:43] offset:256
	global_atomic_add v3, v2, s[42:43] offset:512
	global_atomic_add v3, v2, s[42:43] offset:768
	global_atomic_add v3, v2, s[42:43] offset:1024
	global_atomic_add v3, v2, s[42:43] offset:1280
	global_atomic_add v3, v2, s[42:43] offset:1536
	global_atomic_add v3, v2, s[42:43] offset:1792
	global_atomic_add v3, v2, s[42:43] offset:2048
	global_atomic_add v3, v2, s[42:43] offset:2304
	global_atomic_add v3, v2, s[42:43] offset:2560
	global_atomic_add v3, v2, s[42:43] offset:2816
	global_atomic_add v3, v2, s[42:43] offset:3072
	global_atomic_add v3, v2, s[42:43] offset:3328
	global_atomic_add v3, v2, s[42:43] offset:3584
	global_atomic_add v3, v2, s[42:43] offset:3840

; __device__ __forceinline__ unsigned xb_ld(unsigned* p)              { return __hip_atomic_load(p, __ATOMIC_RELAXED, __HIP_MEMORY_SCOPE_AGENT); }
; __device__ __forceinline__ unsigned xb_add(unsigned* p, unsigned v) { return __hip_atomic_fetch_add(p, v, __ATOMIC_RELAXED, __HIP_MEMORY_SCOPE_AGENT); }
; #define XB_SPIN(cond, bar) do { unsigned _sp = 0; while (cond) { __builtin_amdgcn_s_sleep(1); \
;     if ((++_sp & 255u) == 0u) { if (xb_ld(&(bar)[XB_TMO])) break; if (_sp > XB_SPIN_CAP) { atomicAdd(&(bar)[XB_TMO], 1u); break; } } } } while (0)
; template <bool FLUSH> __device__ __forceinline__ void xcd_barrier(const XcdBarrier& b) {
;     ...
;             if (og + 1u == (tg + 1u) * nx) xb_add(&bar[XB_TOPGEN], 1u);
;             else XB_SPIN(xb_ld(&bar[XB_TOPGEN]) == tg, bar);
;             __builtin_amdgcn_fence(__ATOMIC_ACQUIRE, "agent");
;             xb_add(&bar[XB_XGEN(b.x)], 1u);
;             asm volatile("s_waitcnt vmcnt(0)" ::: "memory");
.LBB0_2227:
	s_or_b64 exec, exec, s[4:5]
	v_mov_b32_e32 v0, 0x2000
	v_mov_b32_e32 v1, 1
	s_waitcnt vmcnt(0)
	buffer_inv sc1
	s_waitcnt vmcnt(0)
